# adds: transposed V image written bank-conflict-free (each lane rotates its 8 packed words by its piece index, per-slot row addresses precomputed)
# baseline (speedup 1.0000x reference)
; DI void attn_phase(LAS unsigned char* lds, bf16_t* QKV, float* LSE, const float* qg, const float* kg, const float* relb, int G, int bid) {
;     ...
;     const int per = (6144 + G - 1) / G; const int u0 = bid * per; int u1 = u0 + per; if (u1 > 6144) u1 = 6144;
;     const int kp2 = tid & 63, vpc = tid >> 6;
;     u32x4 pq[2], pk[2], pv[2];
;     int rn, h, g, d, n; size_t rowbase;
;     if (u0 < u1) { attn_unit_ptrs(u0, rn, h, g, d, n, rowbase);
;         const bf16_t* qp = QKV + (size_t)g * SEC + rowbase * 1024 + h * 64; const bf16_t* kp = qp + 3 * SEC; const bf16_t* vp = qp + 6 * SEC;
; #pragma unroll
;         for (int it = 0; it < 2; ++it) { const int idx = tid + 512 * it, row = idx >> 3, pc = idx & 7; pq[it] = *(const u32x4*)(qp + (size_t)row * 1024 + pc * 8); pk[it] = *(const u32x4*)(kp + (size_t)row * 1024 + pc * 8); }
;         pv[0] = *(const u32x4*)(vp + (size_t)(2 * kp2) * 1024 + vpc * 8); pv[1] = *(const u32x4*)(vp + (size_t)(2 * kp2 + 1) * 1024 + vpc * 8); }
;     ...
;         for (int i = 0; i < 9; ++i) { const int tau = w + i; const int kr = ((((n + 1 + (tau >> 3)) & 1) << 7) | ((tau & 7) << 4)) + fr; f32x4 acc = (f32x4){0.f, 0.f, 0.f, 0.f};
;             const bf16x8 a0 = *(const LAS bf16x8*)(Ks + kr * 72 + 8 * fq), a1 = *(const LAS bf16x8*)(Ks + kr * 72 + 32 + 8 * fq);
;             acc = __builtin_amdgcn_mfma_f32_16x16x32_bf16(a0, qf[0], acc, 0, 0, 0);
;             acc = __builtin_amdgcn_mfma_f32_16x16x32_bf16(a1, qf[1], acc, 0, 0, 0);
;             sc[i] = acc; }
;         float mx = -INFINITY;
;         const LAS float* tb = tab + (16 + fr - 4 * fq - 3);
;         const int dlt = fr - 4 * fq;
;         float bv[9][4];
; #pragma unroll
;         for (int i = 0; i < 9; ++i)
; #pragma unroll
;             for (int j = 0; j < 4; ++j) bv[i][j] = tb[16 * (8 - i) + (3 - j)];
; #pragma unroll
;         for (int i = 0; i < 9; ++i)
; #pragma unroll
;             for (int j = 0; j < 4; ++j) asm volatile("" : "+v"(bv[i][j]));
; #pragma unroll
;         for (int i = 0; i < 9; ++i) { const bool tv = (n > 0) || (w + i >= 8);
; #pragma unroll
;             for (int j = 0; j < 4; ++j) { bool valid = tv;
;                 if (i == 0) valid = valid && (dlt - j <= 0);
;                 if (i == 8) valid = valid && (dlt - j >= 0);
;                 const float v = valid ? sc[i][j] + bv[i][j] : -INFINITY; sc[i][j] = v; mx = fmaxf(mx, v); } }
.LBB0_310:
	s_cmp_gt_i32 s34, 1
	s_mov_b64 s[0:1], -1
	s_cbranch_scc0 .LBB0_331
	v_readlane_b32 s0, v251, 25
	v_readlane_b32 s1, v251, 26
	v_mov_b32_e32 v52, v226
	s_andn2_b64 vcc, exec, s[0:1]
	v_readlane_b32 s2, v251, 28
	s_cbranch_vccnz .LBB0_330
	s_waitcnt vmcnt(0)
	v_lshlrev_b32_e32 v0, 3, v52
	v_and_b32_e32 v24, 56, v0
	v_readlane_b32 s0, v251, 31
	v_lshlrev_b32_e32 v112, 1, v24
	v_readlane_b32 s1, v251, 32
	v_add_u32_e32 v41, 0x200, v52
	v_and_b32_e32 v39, 63, v52
	v_lshl_add_u64 v[8:9], s[0:1], 0, v[112:113]
	v_readlane_b32 s0, v251, 29
	v_readlane_b32 s1, v251, 30
	v_ashrrev_i32_e32 v71, 6, v52
	v_lshrrev_b32_e32 v122, 3, v39
	v_and_b32_e32 v123, 7, v52
	v_lshl_add_u32 v122, v71, 3, v122
	v_ashrrev_i32_e32 v26, 3, v52
	v_lshl_add_u64 v[10:11], s[0:1], 0, v[112:113]
	v_ashrrev_i32_e32 v30, 3, v41
	v_readlane_b32 s0, v251, 33
	v_ashrrev_i32_e32 v27, 31, v26
	v_ashrrev_i32_e32 v31, 31, v30
	v_lshlrev_b32_e32 v16, 12, v122
	v_mov_b32_e32 v17, v113
	v_readlane_b32 s1, v251, 34
	v_lshlrev_b32_e32 v36, 3, v123
	v_lshlrev_b64 v[28:29], 11, v[26:27]
	v_lshlrev_b64 v[32:33], 11, v[30:31]
	v_lshl_add_u64 v[16:17], s[0:1], 0, v[16:17]
	v_ashrrev_i32_e32 v37, 31, v36
	v_lshl_add_u64 v[0:1], v[8:9], 0, v[28:29]
	v_lshl_add_u64 v[4:5], v[10:11], 0, v[28:29]
	v_lshl_add_u64 v[8:9], v[8:9], 0, v[32:33]
	v_lshl_add_u64 v[12:13], v[10:11], 0, v[32:33]
	v_lshl_add_u64 v[20:21], v[36:37], 1, v[16:17]
	global_load_dwordx4 v[0:3], v[0:1], off
	s_nop 0
	global_load_dwordx4 v[4:7], v[4:5], off
	s_nop 0
	global_load_dwordx4 v[8:11], v[8:9], off
	s_nop 0
	global_load_dwordx4 v[12:15], v[12:13], off
	s_nop 0
	global_load_dwordx4 v[16:19], v[20:21], off
	s_nop 0
	global_load_dwordx4 v[20:23], v[20:21], off offset:2048
	v_and_b32_e32 v53, 15, v52
	s_movk_i32 s0, 0xa0
	v_lshlrev_b32_e32 v62, 4, v71
	v_lshlrev_b64 v[56:57], 10, v[30:31]
	v_cmp_gt_i32_e64 s[38:39], s0, v52
	v_add_u32_e32 v25, -16, v52
	s_movk_i32 s0, 0x81
	v_or_b32_e32 v44, v62, v53
	v_and_b32_e32 v31, 48, v52
	v_add_u32_e32 v78, 2, v71
	v_add_u32_e32 v85, 4, v71
	v_add_u32_e32 v92, 6, v71
	v_lshl_add_u32 v38, v39, 2, 0
	v_cmp_gt_u32_e64 s[40:41], s0, v25
	s_movk_i32 s0, 0x1080
	v_add_u32_e32 v46, 0, v31
	v_ashrrev_i32_e32 v45, 31, v44
	v_add_u32_e32 v63, 1, v71
	v_lshlrev_b32_e32 v64, 4, v78
	v_add_u32_e32 v65, 3, v71
	v_lshlrev_b32_e32 v66, 4, v85
	v_add_u32_e32 v67, 5, v71
	v_lshlrev_b32_e32 v68, 4, v92
	v_add_u32_e32 v69, 7, v71
	v_add_u32_e32 v99, 8, v71
	v_bfe_u32 v35, v52, 4, 2
	v_lshlrev_b32_e32 v34, 11, v122
	v_readlane_b32 s34, v250, 5
	v_add_u32_e32 v40, 0, v112
	v_lshlrev_b32_e32 v42, 2, v122
	v_mad_u32_u24 v42, v123, s0, v42
	v_mov_b32_e32 v218, v123
	v_lshlrev_b32_e32 v219, 2, v122
	v_add_u32_e32 v219, 0xd800, v219
	v_mov_b32_e32 v220, v123
	v_and_b32_e32 v220, 7, v220
	v_lshl_add_u32 v220, v123, 3, v220
	v_mad_u32_u24 v194, v220, s81, v219
	v_add_u32_e32 v220, 1, v123
	v_and_b32_e32 v220, 7, v220
	v_lshl_add_u32 v220, v123, 3, v220
	v_mad_u32_u24 v195, v220, s81, v219
	v_add_u32_e32 v220, 2, v123
	v_and_b32_e32 v220, 7, v220
	v_lshl_add_u32 v220, v123, 3, v220
	v_mad_u32_u24 v196, v220, s81, v219
	v_add_u32_e32 v220, 3, v123
	v_and_b32_e32 v220, 7, v220
	v_lshl_add_u32 v220, v123, 3, v220
	v_mad_u32_u24 v197, v220, s81, v219
	v_add_u32_e32 v220, 4, v123
	v_and_b32_e32 v220, 7, v220
	v_lshl_add_u32 v220, v123, 3, v220
	v_mad_u32_u24 v198, v220, s81, v219
	v_add_u32_e32 v220, 5, v123
	v_and_b32_e32 v220, 7, v220
	v_lshl_add_u32 v220, v123, 3, v220
	v_mad_u32_u24 v199, v220, s81, v219
	v_add_u32_e32 v220, 6, v123
	v_and_b32_e32 v220, 7, v220
	v_lshl_add_u32 v220, v123, 3, v220
	v_mad_u32_u24 v200, v220, s81, v219
	v_add_u32_e32 v220, 7, v123
	v_and_b32_e32 v220, 7, v220
	v_lshl_add_u32 v220, v123, 3, v220
	v_mad_u32_u24 v201, v220, s81, v219
	v_mad_u64_u32 v[48:49], s[0:1], v44, s25, v[46:47]
	v_lshlrev_b64 v[50:51], 11, v[44:45]
	v_cmp_gt_u32_e64 s[42:43], 16, v39
	v_ashrrev_i32_e32 v45, 31, v62
	v_mul_lo_u32 v39, v71, s81
	v_lshrrev_b32_e32 v61, 3, v71
	v_and_b32_e32 v106, 0x70, v62
	v_lshrrev_b32_e32 v62, 3, v63
	v_lshlrev_b32_e32 v107, 4, v63
	v_lshrrev_b32_e32 v63, 3, v78
	v_and_b32_e32 v108, 0x70, v64
	v_lshrrev_b32_e32 v64, 3, v65
	v_lshlrev_b32_e32 v109, 4, v65
	v_lshrrev_b32_e32 v65, 3, v85
	v_and_b32_e32 v111, 0x70, v66
	v_lshrrev_b32_e32 v66, 3, v67
	v_lshlrev_b32_e32 v112, 4, v67
	v_lshrrev_b32_e32 v67, 3, v92
	v_and_b32_e32 v116, 0x70, v68
	v_lshrrev_b32_e32 v68, 3, v69
	v_lshlrev_b32_e32 v117, 4, v69
	v_lshrrev_b32_e32 v69, 3, v99
	v_lshlrev_b32_e32 v70, 4, v99
	v_cmp_lt_i32_e64 s[44:45], 7, v71
	v_cmp_lt_i32_e64 s[54:55], 6, v71
	v_cmp_lt_i32_e64 s[56:57], 5, v71
	v_cmp_lt_i32_e64 s[58:59], 4, v71
	v_cmp_lt_i32_e64 s[60:61], 3, v71
	v_cmp_lt_i32_e64 s[62:63], 2, v71
	v_cmp_lt_i32_e64 s[64:65], 1, v71
	v_cmp_lt_i32_e64 s[66:67], 0, v71
	v_cmp_lt_i32_e64 s[68:69], -1, v71
	v_min_i32_e32 v71, 14, v71
	v_min_i32_e32 v78, 14, v78
	v_min_i32_e32 v85, 14, v85
	v_min_i32_e32 v92, 14, v92
	v_min_i32_e32 v99, 14, v99
	v_lshlrev_b64 v[54:55], 10, v[26:27]
	v_lshl_add_u32 v27, v52, 2, s34
	v_or_b32_e32 v31, 16, v53
	v_lshlrev_b32_e32 v110, 2, v35
	v_add_u32_e32 v43, 0x400, v52
	v_add_u32_e32 v47, 0x600, v52
	v_add_u32_e32 v49, 0x800, v52
	v_add_u32_e32 v58, 0xa00, v52
	v_add_u32_e32 v59, 0xc00, v52
	v_add_u32_e32 v52, 0xe00, v52
	v_add_u32_e32 v73, 1, v71
	v_add_u32_e32 v80, 1, v78
	v_add_u32_e32 v87, 1, v85
	v_add_u32_e32 v94, 1, v92
	v_add_u32_e32 v102, 1, v99
	v_sub_u32_e32 v31, v31, v110
	v_ashrrev_i32_e32 v52, 6, v52
	v_and_b32_e32 v118, 0x70, v70
	v_mad_u32_u24 v101, v53, s81, 0
	v_lshrrev_b32_e32 v71, 3, v73
	v_lshlrev_b32_e32 v73, 5, v73
	v_lshrrev_b32_e32 v78, 3, v80
	v_lshlrev_b32_e32 v80, 5, v80
	v_lshrrev_b32_e32 v85, 3, v87
	v_lshlrev_b32_e32 v87, 5, v87
	v_lshrrev_b32_e32 v92, 3, v94
	v_lshlrev_b32_e32 v94, 5, v94
	v_lshrrev_b32_e32 v99, 3, v102
	v_lshlrev_b32_e32 v102, 5, v102
	v_lshlrev_b32_e32 v105, 3, v35
	v_lshl_add_u32 v31, v31, 2, s34
	v_sub_u32_e32 v72, v53, v110
	v_ashrrev_i32_e32 v41, 6, v41
	v_ashrrev_i32_e32 v43, 6, v43
	v_ashrrev_i32_e32 v47, 6, v47
	v_ashrrev_i32_e32 v49, 6, v49
	v_ashrrev_i32_e32 v58, 6, v58
	v_ashrrev_i32_e32 v59, 6, v59
	v_mul_lo_u32 v60, v52, s81
	v_mul_lo_u32 v52, v26, s25
	v_add_u32_e32 v114, 0xd800, v101
	v_lshlrev_b32_e32 v76, 1, v106
	v_and_b32_e32 v77, 0xe0, v73
	v_add_u32_e32 v103, 0x2100, v101
	v_lshlrev_b32_e32 v83, 1, v108
	s_waitcnt lgkmcnt(0)
; #define LAS __attribute__((address_space(3)))
; DI unsigned pk2(float lo, float hi) { f32x2n v = {lo, hi}; bf16x2n b = __builtin_convertvector(v, bf16x2n); return __builtin_bit_cast(unsigned, b); }
; DI float x16_sum(float x) { const unsigned u = __builtin_bit_cast(unsigned, x); auto r = __builtin_amdgcn_permlane16_swap(u, u, false, false); return __builtin_bit_cast(float, (unsigned)r[0]) + __builtin_bit_cast(float, (unsigned)r[1]); }
; DI void attn_phase(LAS unsigned char* lds, bf16_t* QKV, float* LSE, const float* qg, const float* kg, const float* relb, int G, int bid) {
;     ...
;         for (int i = 0; i < 9; ++i) { const bool tv = (n > 0) || (w + i >= 8);
; #pragma unroll
;             for (int j = 0; j < 4; ++j) { bool valid = tv;
;                 if (i == 0) valid = valid && (dlt - j <= 0);
;                 if (i == 8) valid = valid && (dlt - j >= 0);
;                 const float v = valid ? sc[i][j] + bv[i][j] : -INFINITY; sc[i][j] = v; mx = fmaxf(mx, v); } }
;         mx = x16_max(mx); mx = x32_max(mx);
;         float sum = 0.f;
; #pragma unroll
;         for (int i = 0; i < 9; ++i)
; #pragma unroll
;             for (int j = 0; j < 4; ++j) { const float p = __builtin_amdgcn_exp2f(sc[i][j] - mx); sc[i][j] = p; sum += p; }
;         sum = x16_sum(sum); sum = x32_sum(sum);
;         f32x4 o[4];
; #pragma unroll
;         for (int et = 0; et < 4; ++et) o[et] = (f32x4){0.f, 0.f, 0.f, 0.f};
; #pragma unroll
;         for (int pi = 0; pi < 5; ++pi) { const int ia = 2 * pi, ib = (2 * pi + 1 < 9) ? 2 * pi + 1 : 8;
;             u32x4 pw; pw.x = pk2(sc[ia][0], sc[ia][1]); pw.y = pk2(sc[ia][2], sc[ia][3]);
;             if (2 * pi + 1 < 9) { pw.z = pk2(sc[ib][0], sc[ib][1]); pw.w = pk2(sc[ib][2], sc[ib][3]); } else { pw.z = 0u; pw.w = 0u; }
;             const bf16x8 pb = __builtin_bit_cast(bf16x8, pw);
;             const int ta = w + ia; int tb = w + 2 * pi + 1; if (tb > 15) tb = 15;
;             const int ca = ((((n + 1 + (ta >> 3)) & 1) << 7) | ((ta & 7) << 4)) + 4 * fq, cb = ((((n + 1 + (tb >> 3)) & 1) << 7) | ((tb & 7) << 4)) + 4 * fq;
; #pragma unroll
;             for (int et = 0; et < 4; ++et) { const LAS bf16_t* vr = Vt + (16 * et + fr) * 264;
;                 const u32x2 lo = *(const LAS u32x2*)(vr + ca), hi = *(const LAS u32x2*)(vr + cb);
	v_and_b32_e32 v84, 0xe0, v80
	v_lshlrev_b32_e32 v90, 1, v111
	v_and_b32_e32 v91, 0xe0, v87
	v_lshlrev_b32_e32 v97, 1, v116
	v_and_b32_e32 v98, 0xe0, v94
	v_lshlrev_b32_e32 v104, 1, v118
	v_and_b32_e32 v115, 0xe0, v102
	v_mul_lo_u32 v120, v30, s25
	s_movk_i32 s0, 0x70
	v_add_u32_e32 v35, -12, v31
	v_mul_lo_u32 v41, v41, s81
	v_mul_lo_u32 v43, v43, s81
	v_mul_lo_u32 v47, v47, s81
	v_mul_lo_u32 v49, v49, s81
	v_mul_lo_u32 v58, v58, s81
	v_mul_lo_u32 v59, v59, s81
	v_add_u32_e32 v70, -4, v31
	v_cmp_gt_i32_e64 s[46:47], 1, v72
	v_cmp_gt_i32_e64 s[48:49], 2, v72
	v_cmp_gt_i32_e64 s[50:51], 3, v72
	v_cmp_gt_i32_e64 s[52:53], 4, v72
	s_mov_b32 s87, 0
	v_cmp_lt_i32_e64 s[70:71], -1, v72
	v_cmp_lt_i32_e64 s[72:73], 0, v72
	v_cmp_lt_i32_e64 s[74:75], 1, v72
	v_cmp_lt_i32_e64 s[76:77], 2, v72
	v_add3_u32 v72, v101, v76, v105
	v_add3_u32 v73, v101, v77, v105
	v_add3_u32 v74, v103, v76, v105
	v_add3_u32 v75, v103, v77, v105
	v_add3_u32 v76, v114, v76, v105
	v_add3_u32 v77, v114, v77, v105
	v_add3_u32 v79, v101, v83, v105
	v_add3_u32 v80, v101, v84, v105
	v_add3_u32 v81, v103, v83, v105
	v_add3_u32 v82, v103, v84, v105
	v_add3_u32 v83, v114, v83, v105
	v_add3_u32 v84, v114, v84, v105
	v_add3_u32 v86, v101, v90, v105
	v_add3_u32 v87, v101, v91, v105
	v_add3_u32 v88, v103, v90, v105
	v_add3_u32 v89, v103, v91, v105
	v_add3_u32 v90, v114, v90, v105
	v_add3_u32 v91, v114, v91, v105
	v_add3_u32 v93, v101, v97, v105
	v_add3_u32 v94, v101, v98, v105
	v_add3_u32 v95, v103, v97, v105
	v_add3_u32 v96, v103, v98, v105
	v_add3_u32 v97, v114, v97, v105
	v_add3_u32 v98, v114, v98, v105
	v_add3_u32 v100, v101, v104, v105
	v_add3_u32 v101, v101, v115, v105
	v_add3_u32 v102, v103, v104, v105
	v_add3_u32 v103, v103, v115, v105
	v_add3_u32 v104, v114, v104, v105
	v_add3_u32 v105, v114, v115, v105
	v_or_b32_e32 v106, v106, v53
	v_and_or_b32 v107, v107, s0, v53
	v_or_b32_e32 v108, v108, v53
	v_and_or_b32 v109, v109, s0, v53
	v_or_b32_e32 v114, v111, v53
	v_and_or_b32 v115, v112, s0, v53
	v_or_b32_e32 v116, v116, v53
	v_and_or_b32 v117, v117, s0, v53
	v_or_b32_e32 v118, v118, v53
	v_add_u32_e32 v119, v40, v52
	v_add_u32_e32 v120, v40, v120
	v_lshlrev_b64 v[52:53], 1, v[54:55]
	v_lshlrev_b64 v[54:55], 1, v[56:57]
	v_lshlrev_b32_e32 v56, 1, v110
	v_readlane_b32 s78, v251, 27
	s_branch .LBB0_314

; DI void lbar() { asm volatile("s_waitcnt lgkmcnt(0)" ::: "memory"); __builtin_amdgcn_s_barrier(); asm volatile("" ::: "memory"); }
; DI void attn_phase(LAS unsigned char* lds, bf16_t* QKV, float* LSE, const float* qg, const float* kg, const float* relb, int G, int bid) {
;     ...
;         vt_store(Vt32 + (8 * vpc) * 132 + slot * 64 + kp2, pv[0], pv[1]);
;         lbar();
;         if (u + 1 < u1) {
;             int rn2, h2, g2, d2, n2; size_t rb2; attn_unit_ptrs(u + 1, rn2, h2, g2, d2, n2, rb2);
;             const bf16_t* qp2 = QKV + (size_t)g2 * SEC + rb2 * 1024 + h2 * 64; const bf16_t* kp2p = qp2 + 3 * SEC; const bf16_t* vp2 = qp2 + 6 * SEC;
; #pragma unroll
;             for (int it = 0; it < 2; ++it) { const int idx = tid + 512 * it, row = idx >> 3, pc = idx & 7; pq[it] = *(const u32x4*)(qp2 + (size_t)row * 1024 + pc * 8); pk[it] = *(const u32x4*)(kp2p + (size_t)row * 1024 + pc * 8); }
;             pv[0] = *(const u32x4*)(vp2 + (size_t)(2 * kp2) * 1024 + vpc * 8); pv[1] = *(const u32x4*)(vp2 + (size_t)(2 * kp2 + 1) * 1024 + vpc * 8);
;         }
.Lat_join:
	s_lshl_b32 s83, s82, 8
	s_mov_b32 s82, 0xffff
	v_lshlrev_b32_e32 v202, 16, v20
	v_lshrrev_b32_e32 v203, 16, v16
	v_and_or_b32 v202, v16, s82, v202
	v_and_or_b32 v203, v20, s27, v203
	v_lshlrev_b32_e32 v204, 16, v21
	v_lshrrev_b32_e32 v205, 16, v17
	v_and_or_b32 v204, v17, s82, v204
	v_and_or_b32 v205, v21, s27, v205
	v_lshlrev_b32_e32 v206, 16, v22
	v_lshrrev_b32_e32 v207, 16, v18
	v_and_or_b32 v206, v18, s82, v206
	v_and_or_b32 v207, v22, s27, v207
	v_lshlrev_b32_e32 v208, 16, v23
	v_lshrrev_b32_e32 v209, 16, v19
	v_and_or_b32 v208, v19, s82, v208
	v_and_or_b32 v209, v23, s27, v209
	v_and_b32_e32 v110, 1, v218
	v_cmp_ne_u32_e32 vcc, 0, v110
	v_cndmask_b32_e32 v210, v202, v203, vcc
	v_cndmask_b32_e32 v211, v203, v204, vcc
	v_cndmask_b32_e32 v212, v204, v205, vcc
	v_cndmask_b32_e32 v213, v205, v206, vcc
	v_cndmask_b32_e32 v214, v206, v207, vcc
	v_cndmask_b32_e32 v215, v207, v208, vcc
	v_cndmask_b32_e32 v216, v208, v209, vcc
	v_cndmask_b32_e32 v217, v209, v202, vcc
	v_and_b32_e32 v110, 2, v218
	v_cmp_ne_u32_e32 vcc, 0, v110
	v_cndmask_b32_e32 v202, v210, v212, vcc
	v_cndmask_b32_e32 v203, v211, v213, vcc
	v_cndmask_b32_e32 v204, v212, v214, vcc
	v_cndmask_b32_e32 v205, v213, v215, vcc
	v_cndmask_b32_e32 v206, v214, v216, vcc
	v_cndmask_b32_e32 v207, v215, v217, vcc
	v_cndmask_b32_e32 v208, v216, v210, vcc
	v_cndmask_b32_e32 v209, v217, v211, vcc
	v_and_b32_e32 v110, 4, v218
	v_cmp_ne_u32_e32 vcc, 0, v110
	v_cndmask_b32_e32 v210, v202, v206, vcc
	v_cndmask_b32_e32 v211, v203, v207, vcc
	v_cndmask_b32_e32 v212, v204, v208, vcc
	v_cndmask_b32_e32 v213, v205, v209, vcc
	v_cndmask_b32_e32 v214, v206, v202, vcc
	v_cndmask_b32_e32 v215, v207, v203, vcc
	v_cndmask_b32_e32 v216, v208, v204, vcc
	v_cndmask_b32_e32 v217, v209, v205, vcc
	v_add_u32_e32 v110, s83, v194
	ds_write_b32 v110, v210
	v_add_u32_e32 v111, s83, v195
	ds_write_b32 v111, v211
	v_add_u32_e32 v112, s83, v196
	ds_write_b32 v112, v212
	v_add_u32_e32 v57, s83, v197
	ds_write_b32 v57, v213
	v_add_u32_e32 v110, s83, v198
	ds_write_b32 v110, v214
	v_add_u32_e32 v111, s83, v199
	ds_write_b32 v111, v215
	v_add_u32_e32 v112, s83, v200
	ds_write_b32 v112, v216
	v_add_u32_e32 v57, s83, v201
	ds_write_b32 v57, v217
	s_waitcnt lgkmcnt(0)
	s_barrier
	s_add_i32 s2, s2, 1
	v_readlane_b32 s82, v251, 24
	s_cmp_ge_i32 s2, s82
	s_cbranch_scc1 .LBB0_328
	s_ashr_i32 s82, s2, 10
	s_mul_hi_i32 s83, s82, 0x55555556
	s_lshr_b32 s88, s83, 31
	s_add_i32 s83, s83, s88
	s_and_b32 s90, s2, 0x3c0
	s_mul_i32 s83, s83, 3
	s_mul_hi_i32 s2, s2, 0x2aaaaaab
	s_sub_i32 s82, s82, s83
	s_lshr_b32 s83, s2, 31
	s_lshr_b32 s2, s2, 9
	s_add_i32 s2, s2, s83
	s_add_i32 s83, s78, 0x80
	s_lshl_b32 s2, s2, 13
	s_and_b32 s83, s83, 0x1f80
	s_or_b32 s88, s83, s2
	s_ashr_i32 s83, s82, 31
	s_ashr_i32 s89, s88, 31
	s_lshl_b64 s[82:83], s[82:83], 25
	s_add_u32 s2, s28, s82
	s_addc_u32 s91, s29, s83
	s_lshl_b64 s[82:83], s[88:89], 11
	s_add_u32 s2, s2, s82
	s_addc_u32 s83, s91, s83
	s_lshl_b32 s82, s90, 1
	s_add_u32 s82, s2, s82
	s_addc_u32 s83, s83, 0
	v_lshlrev_b32_e32 v112, 1, v24
	v_lshl_add_u64 v[8:9], s[82:83], 0, v[112:113]
	v_lshlrev_b32_e32 v112, 1, v34
	v_lshl_add_u64 v[16:17], s[82:83], 0, v[112:113]
	s_mov_b64 s[88:89], 0x6000000
	v_lshl_add_u64 v[16:17], v[36:37], 1, v[16:17]
	s_mov_b64 s[82:83], 0xc000000
	v_lshl_add_u64 v[10:11], v[8:9], 0, s[88:89]
	v_lshl_add_u64 v[20:21], v[16:17], 0, s[82:83]
	v_add_co_u32_e32 v16, vcc, 0xc000000, v16
	v_lshl_add_u64 v[0:1], v[8:9], 0, v[52:53]
	v_lshl_add_u64 v[4:5], v[10:11], 0, v[52:53]
	v_lshl_add_u64 v[8:9], v[8:9], 0, v[54:55]
	v_lshl_add_u64 v[12:13], v[10:11], 0, v[54:55]
	v_addc_co_u32_e32 v17, vcc, 0, v17, vcc
	global_load_dwordx4 v[0:3], v[0:1], off
	s_nop 0
	global_load_dwordx4 v[4:7], v[4:5], off
	s_nop 0
	global_load_dwordx4 v[8:11], v[8:9], off
	s_nop 0
	global_load_dwordx4 v[12:15], v[12:13], off
	s_nop 0
	global_load_dwordx4 v[16:19], v[16:17], off
	s_nop 0
	global_load_dwordx4 v[20:23], v[20:21], off offset:2048
